# P1 in-projection epilogue: hand-written straight-line fast path (one scalar dispatch per tile, 16 x pack/sigmoid + 16-byte store via SGPR base), original path only for the last N tile
# baseline (speedup 1.0000x reference)
;     __device__ __forceinline__ void operator()(const Acc& acc, const Unit& u, int wr, int wc, int fr, int fq) const {
;         const int d = wc * 32 + 8 * fq;
; #pragma unroll
;         for (int bj = 0; bj < 2; ++bj) {
;             const int blk = u.pn * 2 + bj;
;             if (blk >= 77) continue;
;             bf16_t* base; size_t bstride; int kind = 0;
;             if (blk < 8)       { base = (bf16_t*)(ws + WS_QN) + (size_t)blk * SEQ * 128; bstride = (size_t)8 * SEQ * 128; }
;             else if (blk < 10) { base = (bf16_t*)(ws + WS_KC) + (size_t)(blk - 8) * KCROWS * 128; bstride = (size_t)2 * KCROWS * 128; }
;             else if (blk < 12) { base = (bf16_t*)(ws + WS_VC) + (size_t)(blk - 10) * KCROWS * 128; bstride = (size_t)2 * KCROWS * 128; }
;             else if (blk < 14) { base = (bf16_t*)(ws + WS_KSL) + (size_t)(blk - 12) * SEQ * 128; bstride = (size_t)2 * SEQ * 128; }
;             else if (blk < 16) { base = (bf16_t*)(ws + WS_VSL) + (size_t)(blk - 14) * SEQ * 128; bstride = (size_t)2 * SEQ * 128; }
;             else if (blk < 18) { base = (bf16_t*)(ws + WS_KW) + (size_t)(blk - 16) * SEQ * 128; bstride = (size_t)2 * SEQ * 128; }
;             else if (blk < 20) { base = (bf16_t*)(ws + WS_VW) + (size_t)(blk - 18) * SEQ * 128; bstride = (size_t)2 * SEQ * 128; }
;             else if (blk < 28) { base = (bf16_t*)(ws + WS_QD) + (size_t)(blk - 20) * SEQ * 128; bstride = (size_t)8 * SEQ * 128; }
;             else if (blk < 36) { base = (bf16_t*)(ws + WS_KD) + (size_t)(blk - 28) * SEQ * 128; bstride = (size_t)8 * SEQ * 128; }
;             else if (blk < 44) { base = (bf16_t*)(ws + WS_VD) + (size_t)(blk - 36) * SEQ * 128; bstride = (size_t)8 * SEQ * 128; }
;             else if (blk < 76) { base = (bf16_t*)(ws + WS_GM) + (size_t)(blk - 44) * 128; bstride = 0; kind = 1; }
;             else               { base = nullptr; bstride = 0; kind = 2; }
; #pragma unroll
;             for (int ai = 0; ai < 2; ++ai)
; #pragma unroll
;                 for (int m = 0; m < 4; ++m) {
;                     const int row = u.pm * 256 + ai * 128 + wr * 64 + m * 16 + fr;
;                     f32x4 v0 = acc[ai][bj][m][0], v1 = acc[ai][bj][m][1];
;                     if (kind == 0) {
;                         const int b = row >> 14, s = row & (SEQ - 1);
;                         *(u32x4*)(base + (size_t)b * bstride + (size_t)s * 128 + d) = pack8v(v0, v1);
.LBB0_160:
	s_cmp_gt_i32 s54, 37
	s_cbranch_scc1 .Lp1e_orig
	s_ashr_i32 s49, s44, 6
	s_lshl_b32 s56, s54, 1
	s_ashr_i32 s72, s49, 31
	s_cmp_gt_i32 s54, 21
	s_cbranch_scc1 .Lp1e_gate
	s_and_b32 vcc_hi, s44, 63
	s_lshl_b32 vcc_hi, vcc_hi, 16
	s_mov_b32 vcc_lo, 0x400000
	s_cmp_gt_i32 s54, 3
	s_cbranch_scc1 .Lp1e_a1
	s_lshl_b32 s57, s54, 23
	s_lshl_b32 s98, s49, 25
	s_add_u32 s57, s57, s98
	s_branch .Lp1e_k0
.Lp1e_a1:
	s_cmp_gt_i32 s54, 5
	s_cbranch_scc1 .Lp1e_a2
	s_sub_i32 s57, s54, 4
	s_mul_i32 s57, s57, 0x1004000
	s_mul_i32 s98, s49, 0x802000
	s_add_u32 s57, s57, s98
	s_add_u32 s57, s57, 0x4000000
	s_mov_b32 vcc_lo, 0x401000
	s_branch .Lp1e_k0
.Lp1e_a2:
	s_cmp_gt_i32 s54, 9
	s_cbranch_scc1 .Lp1e_a3
	s_sub_i32 s57, s54, 6
	s_lshl_b32 s57, s57, 24
	s_lshl_b32 s98, s49, 23
	s_add_u32 s57, s57, s98
	s_add_u32 s57, s57, 0x6008000
	s_branch .Lp1e_k0
.Lp1e_a3:
	s_sub_i32 s57, s54, 10
	s_lshr_b32 s98, s57, 2
	s_lshl_b32 s98, s98, 26
	s_and_b32 s57, s57, 3
	s_lshl_b32 s57, s57, 23
	s_add_u32 s57, s57, s98
	s_lshl_b32 s98, s49, 25
	s_add_u32 s57, s57, s98
	s_add_u32 s57, s57, 0xa008000
.Lp1e_k0:
	s_add_u32 s57, s57, vcc_hi
	s_add_u32 s98, s18, 0xfe40800
	s_addc_u32 s99, s19, 0
	s_add_u32 s98, s98, s57
	s_addc_u32 s99, s99, 0
	s_add_u32 s100, s98, 0x8000
	s_addc_u32 s101, s99, 0
	v_lshlrev_b32_e32 v236, 1, v138
	v_lshl_add_u32 v236, v156, 8, v236
	v_add_u32_e32 v237, 0x1000, v236
	v_add_u32_e32 v238, 0x2000, v236
	v_add_u32_e32 v239, 0x3000, v236
	v_cvt_pk_bf16_f32 v170, v124, v125
	v_cvt_pk_bf16_f32 v171, v126, v127
	v_cvt_pk_bf16_f32 v172, v120, v121
	v_cvt_pk_bf16_f32 v173, v122, v123
	global_store_dwordx4 v236, v[170:173], s[98:99]
	v_cvt_pk_bf16_f32 v174, v116, v117
	v_cvt_pk_bf16_f32 v175, v118, v119
	v_cvt_pk_bf16_f32 v176, v112, v113
	v_cvt_pk_bf16_f32 v177, v114, v115
	global_store_dwordx4 v237, v[174:177], s[98:99]
	v_cvt_pk_bf16_f32 v178, v108, v109
	v_cvt_pk_bf16_f32 v179, v110, v111
	v_cvt_pk_bf16_f32 v180, v104, v105
	v_cvt_pk_bf16_f32 v181, v106, v107
	global_store_dwordx4 v238, v[178:181], s[98:99]
	v_cvt_pk_bf16_f32 v182, v100, v101
	v_cvt_pk_bf16_f32 v183, v102, v103
	v_cvt_pk_bf16_f32 v184, v96, v97
	v_cvt_pk_bf16_f32 v185, v98, v99
	global_store_dwordx4 v239, v[182:185], s[98:99]
	v_cvt_pk_bf16_f32 v186, v92, v93
	v_cvt_pk_bf16_f32 v187, v94, v95
	v_cvt_pk_bf16_f32 v188, v88, v89
	v_cvt_pk_bf16_f32 v189, v90, v91
	global_store_dwordx4 v236, v[186:189], s[100:101]
	v_cvt_pk_bf16_f32 v212, v84, v85
	v_cvt_pk_bf16_f32 v213, v86, v87
	v_cvt_pk_bf16_f32 v214, v80, v81
	v_cvt_pk_bf16_f32 v215, v82, v83
	global_store_dwordx4 v237, v[212:215], s[100:101]
	v_cvt_pk_bf16_f32 v216, v76, v77
	v_cvt_pk_bf16_f32 v217, v78, v79
	v_cvt_pk_bf16_f32 v218, v72, v73
	v_cvt_pk_bf16_f32 v219, v74, v75
	global_store_dwordx4 v238, v[216:219], s[100:101]
	v_cvt_pk_bf16_f32 v220, v68, v69
	v_cvt_pk_bf16_f32 v221, v70, v71
	v_cvt_pk_bf16_f32 v222, v64, v65
	v_cvt_pk_bf16_f32 v223, v66, v67
	global_store_dwordx4 v239, v[220:223], s[100:101]
	s_add_u32 s98, s98, vcc_lo
	s_addc_u32 s99, s99, 0
	s_add_u32 s100, s100, vcc_lo
	s_addc_u32 s101, s101, 0
	v_cvt_pk_bf16_f32 v224, v60, v61
	v_cvt_pk_bf16_f32 v225, v62, v63
	v_cvt_pk_bf16_f32 v226, v56, v57
	v_cvt_pk_bf16_f32 v227, v58, v59
	global_store_dwordx4 v236, v[224:227], s[98:99]
	v_cvt_pk_bf16_f32 v228, v52, v53
	v_cvt_pk_bf16_f32 v229, v54, v55
	v_cvt_pk_bf16_f32 v230, v48, v49
	v_cvt_pk_bf16_f32 v231, v50, v51
	global_store_dwordx4 v237, v[228:231], s[98:99]
	v_cvt_pk_bf16_f32 v170, v44, v45
	v_cvt_pk_bf16_f32 v171, v46, v47
	v_cvt_pk_bf16_f32 v172, v40, v41
	v_cvt_pk_bf16_f32 v173, v42, v43
	global_store_dwordx4 v238, v[170:173], s[98:99]
	v_cvt_pk_bf16_f32 v174, v36, v37
	v_cvt_pk_bf16_f32 v175, v38, v39
	v_cvt_pk_bf16_f32 v176, v32, v33
	v_cvt_pk_bf16_f32 v177, v34, v35
	global_store_dwordx4 v239, v[174:177], s[98:99]
	v_cvt_pk_bf16_f32 v178, v28, v29
	v_cvt_pk_bf16_f32 v179, v30, v31
	v_cvt_pk_bf16_f32 v180, v24, v25
	v_cvt_pk_bf16_f32 v181, v26, v27
	global_store_dwordx4 v236, v[178:181], s[100:101]
	v_cvt_pk_bf16_f32 v182, v20, v21
	v_cvt_pk_bf16_f32 v183, v22, v23
	v_cvt_pk_bf16_f32 v184, v16, v17
	v_cvt_pk_bf16_f32 v185, v18, v19
	global_store_dwordx4 v237, v[182:185], s[100:101]
	v_cvt_pk_bf16_f32 v186, v12, v13
	v_cvt_pk_bf16_f32 v187, v14, v15
	v_cvt_pk_bf16_f32 v188, v8, v9
	v_cvt_pk_bf16_f32 v189, v10, v11
	global_store_dwordx4 v238, v[186:189], s[100:101]
	v_cvt_pk_bf16_f32 v212, v4, v5
	v_cvt_pk_bf16_f32 v213, v6, v7
	v_cvt_pk_bf16_f32 v214, v0, v1
	v_cvt_pk_bf16_f32 v215, v2, v3
	global_store_dwordx4 v239, v[212:215], s[100:101]
	s_branch .LBB0_290
; __device__ __forceinline__ u32x4 pack8v(f32x4 a, f32x4 b) { u32x4 w; w.x = cvtpk(a[0], a[1]); w.y = cvtpk(a[2], a[3]); w.z = cvtpk(b[0], b[1]); w.w = cvtpk(b[2], b[3]); return w; }
; __device__ __forceinline__ float sigmoidf_(float x) { return __builtin_amdgcn_rcpf(1.f + __builtin_amdgcn_exp2f(-1.4426950408889634f * x)); }
;     __device__ __forceinline__ void operator()(const Acc& acc, const Unit& u, int wr, int wc, int fr, int fq) const {
;     ...
;                     } else if (kind == 1) {
; #pragma unroll
;                         for (int e = 0; e < 4; ++e) { v0[e] = sigmoidf_(v0[e]); v1[e] = sigmoidf_(v1[e]); }
;                         __builtin_nontemporal_store(pack8v(v0, v1), (u32x4*)(base + (size_t)row * 4096 + d));
.Lp1e_gate:
	s_sub_i32 s57, s54, 22
	s_lshl_b32 s57, s57, 9
	s_lshl_b32 s98, s44, 21
	s_add_u32 s57, s57, s98
	s_add_u32 s98, s18, 0x25e48800
	s_addc_u32 s99, s19, 0
	s_add_u32 s98, s98, s57
	s_addc_u32 s99, s99, 0
	s_add_u32 s100, s98, 0x100000
	s_addc_u32 s101, s99, 0
	v_lshlrev_b32_e32 v236, 1, v138
	v_lshl_add_u32 v236, v156, 13, v236
	v_add_u32_e32 v237, 0x20000, v236
	v_add_u32_e32 v238, 0x40000, v236
	v_add_u32_e32 v239, 0x60000, v236
	v_mul_f32_e32 v170, 0xbfb8aa3b, v124
	v_mul_f32_e32 v171, 0xbfb8aa3b, v125
	v_mul_f32_e32 v172, 0xbfb8aa3b, v126
	v_mul_f32_e32 v173, 0xbfb8aa3b, v127
	v_mul_f32_e32 v174, 0xbfb8aa3b, v120
	v_mul_f32_e32 v175, 0xbfb8aa3b, v121
	v_mul_f32_e32 v176, 0xbfb8aa3b, v122
	v_mul_f32_e32 v177, 0xbfb8aa3b, v123
	v_exp_f32_e32 v170, v170
	v_exp_f32_e32 v171, v171
	v_exp_f32_e32 v172, v172
	v_exp_f32_e32 v173, v173
	v_exp_f32_e32 v174, v174
	v_exp_f32_e32 v175, v175
	v_exp_f32_e32 v176, v176
	v_exp_f32_e32 v177, v177
	v_add_f32_e32 v170, 1.0, v170
	v_add_f32_e32 v171, 1.0, v171
	v_add_f32_e32 v172, 1.0, v172
	v_add_f32_e32 v173, 1.0, v173
	v_add_f32_e32 v174, 1.0, v174
	v_add_f32_e32 v175, 1.0, v175
	v_add_f32_e32 v176, 1.0, v176
	v_add_f32_e32 v177, 1.0, v177
	v_rcp_f32_e32 v170, v170
	v_rcp_f32_e32 v171, v171
	v_rcp_f32_e32 v172, v172
	v_rcp_f32_e32 v173, v173
	v_rcp_f32_e32 v174, v174
	v_rcp_f32_e32 v175, v175
	v_rcp_f32_e32 v176, v176
	v_rcp_f32_e32 v177, v177
	v_cvt_pk_bf16_f32 v170, v170, v171
	v_cvt_pk_bf16_f32 v171, v172, v173
	v_cvt_pk_bf16_f32 v172, v174, v175
	v_cvt_pk_bf16_f32 v173, v176, v177
	global_store_dwordx4 v236, v[170:173], s[98:99] nt
	v_mul_f32_e32 v178, 0xbfb8aa3b, v116
	v_mul_f32_e32 v179, 0xbfb8aa3b, v117
	v_mul_f32_e32 v180, 0xbfb8aa3b, v118
	v_mul_f32_e32 v181, 0xbfb8aa3b, v119
	v_mul_f32_e32 v182, 0xbfb8aa3b, v112
	v_mul_f32_e32 v183, 0xbfb8aa3b, v113
	v_mul_f32_e32 v184, 0xbfb8aa3b, v114
	v_mul_f32_e32 v185, 0xbfb8aa3b, v115
	v_exp_f32_e32 v178, v178
	v_exp_f32_e32 v179, v179
	v_exp_f32_e32 v180, v180
	v_exp_f32_e32 v181, v181
	v_exp_f32_e32 v182, v182
	v_exp_f32_e32 v183, v183
	v_exp_f32_e32 v184, v184
	v_exp_f32_e32 v185, v185
	v_add_f32_e32 v178, 1.0, v178
	v_add_f32_e32 v179, 1.0, v179
	v_add_f32_e32 v180, 1.0, v180
	v_add_f32_e32 v181, 1.0, v181
	v_add_f32_e32 v182, 1.0, v182
	v_add_f32_e32 v183, 1.0, v183
	v_add_f32_e32 v184, 1.0, v184
	v_add_f32_e32 v185, 1.0, v185
	v_rcp_f32_e32 v178, v178
	v_rcp_f32_e32 v179, v179
	v_rcp_f32_e32 v180, v180
	v_rcp_f32_e32 v181, v181
	v_rcp_f32_e32 v182, v182
	v_rcp_f32_e32 v183, v183
	v_rcp_f32_e32 v184, v184
	v_rcp_f32_e32 v185, v185
	v_cvt_pk_bf16_f32 v178, v178, v179
	v_cvt_pk_bf16_f32 v179, v180, v181
	v_cvt_pk_bf16_f32 v180, v182, v183
	v_cvt_pk_bf16_f32 v181, v184, v185
	global_store_dwordx4 v237, v[178:181], s[98:99] nt
	v_mul_f32_e32 v186, 0xbfb8aa3b, v108
	v_mul_f32_e32 v187, 0xbfb8aa3b, v109
	v_mul_f32_e32 v188, 0xbfb8aa3b, v110
	v_mul_f32_e32 v189, 0xbfb8aa3b, v111
	v_mul_f32_e32 v212, 0xbfb8aa3b, v104
	v_mul_f32_e32 v213, 0xbfb8aa3b, v105
	v_mul_f32_e32 v214, 0xbfb8aa3b, v106
	v_mul_f32_e32 v215, 0xbfb8aa3b, v107
	v_exp_f32_e32 v186, v186
	v_exp_f32_e32 v187, v187
	v_exp_f32_e32 v188, v188
	v_exp_f32_e32 v189, v189
	v_exp_f32_e32 v212, v212
	v_exp_f32_e32 v213, v213
	v_exp_f32_e32 v214, v214
	v_exp_f32_e32 v215, v215
	v_add_f32_e32 v186, 1.0, v186
	v_add_f32_e32 v187, 1.0, v187
	v_add_f32_e32 v188, 1.0, v188
	v_add_f32_e32 v189, 1.0, v189
	v_add_f32_e32 v212, 1.0, v212
	v_add_f32_e32 v213, 1.0, v213
	v_add_f32_e32 v214, 1.0, v214
	v_add_f32_e32 v215, 1.0, v215
	v_rcp_f32_e32 v186, v186
	v_rcp_f32_e32 v187, v187
	v_rcp_f32_e32 v188, v188
	v_rcp_f32_e32 v189, v189
	v_rcp_f32_e32 v212, v212
	v_rcp_f32_e32 v213, v213
	v_rcp_f32_e32 v214, v214
	v_rcp_f32_e32 v215, v215
	v_cvt_pk_bf16_f32 v186, v186, v187
	v_cvt_pk_bf16_f32 v187, v188, v189
	v_cvt_pk_bf16_f32 v188, v212, v213
	v_cvt_pk_bf16_f32 v189, v214, v215
	global_store_dwordx4 v238, v[186:189], s[98:99] nt
	v_mul_f32_e32 v216, 0xbfb8aa3b, v100
	v_mul_f32_e32 v217, 0xbfb8aa3b, v101
	v_mul_f32_e32 v218, 0xbfb8aa3b, v102
	v_mul_f32_e32 v219, 0xbfb8aa3b, v103
	v_mul_f32_e32 v220, 0xbfb8aa3b, v96
	v_mul_f32_e32 v221, 0xbfb8aa3b, v97
	v_mul_f32_e32 v222, 0xbfb8aa3b, v98
	v_mul_f32_e32 v223, 0xbfb8aa3b, v99
	v_exp_f32_e32 v216, v216
	v_exp_f32_e32 v217, v217
	v_exp_f32_e32 v218, v218
	v_exp_f32_e32 v219, v219
	v_exp_f32_e32 v220, v220
	v_exp_f32_e32 v221, v221
	v_exp_f32_e32 v222, v222
	v_exp_f32_e32 v223, v223
	v_add_f32_e32 v216, 1.0, v216
	v_add_f32_e32 v217, 1.0, v217
	v_add_f32_e32 v218, 1.0, v218
	v_add_f32_e32 v219, 1.0, v219
	v_add_f32_e32 v220, 1.0, v220
	v_add_f32_e32 v221, 1.0, v221
	v_add_f32_e32 v222, 1.0, v222
	v_add_f32_e32 v223, 1.0, v223
	v_rcp_f32_e32 v216, v216
	v_rcp_f32_e32 v217, v217
	v_rcp_f32_e32 v218, v218
	v_rcp_f32_e32 v219, v219
	v_rcp_f32_e32 v220, v220
	v_rcp_f32_e32 v221, v221
	v_rcp_f32_e32 v222, v222
	v_rcp_f32_e32 v223, v223
	v_cvt_pk_bf16_f32 v216, v216, v217
	v_cvt_pk_bf16_f32 v217, v218, v219
	v_cvt_pk_bf16_f32 v218, v220, v221
	v_cvt_pk_bf16_f32 v219, v222, v223
	global_store_dwordx4 v239, v[216:219], s[98:99] nt
	v_mul_f32_e32 v224, 0xbfb8aa3b, v92
	v_mul_f32_e32 v225, 0xbfb8aa3b, v93
	v_mul_f32_e32 v226, 0xbfb8aa3b, v94
	v_mul_f32_e32 v227, 0xbfb8aa3b, v95
	v_mul_f32_e32 v228, 0xbfb8aa3b, v88
	v_mul_f32_e32 v229, 0xbfb8aa3b, v89
	v_mul_f32_e32 v230, 0xbfb8aa3b, v90
	v_mul_f32_e32 v231, 0xbfb8aa3b, v91
	v_exp_f32_e32 v224, v224
	v_exp_f32_e32 v225, v225
	v_exp_f32_e32 v226, v226
	v_exp_f32_e32 v227, v227
	v_exp_f32_e32 v228, v228
	v_exp_f32_e32 v229, v229
	v_exp_f32_e32 v230, v230
	v_exp_f32_e32 v231, v231
	v_add_f32_e32 v224, 1.0, v224
; __device__ __forceinline__ float sigmoidf_(float x) { return __builtin_amdgcn_rcpf(1.f + __builtin_amdgcn_exp2f(-1.4426950408889634f * x)); }
; __device__ __forceinline__ u32x4 pack8v(f32x4 a, f32x4 b) { u32x4 w; w.x = cvtpk(a[0], a[1]); w.y = cvtpk(a[2], a[3]); w.z = cvtpk(b[0], b[1]); w.w = cvtpk(b[2], b[3]); return w; }
;     __device__ __forceinline__ void operator()(const Acc& acc, const Unit& u, int wr, int wc, int fr, int fq) const {
;     ...
;                     } else if (kind == 1) {
; #pragma unroll
;                         for (int e = 0; e < 4; ++e) { v0[e] = sigmoidf_(v0[e]); v1[e] = sigmoidf_(v1[e]); }
;                         __builtin_nontemporal_store(pack8v(v0, v1), (u32x4*)(base + (size_t)row * 4096 + d));
	v_add_f32_e32 v225, 1.0, v225
	v_add_f32_e32 v226, 1.0, v226
	v_add_f32_e32 v227, 1.0, v227
	v_add_f32_e32 v228, 1.0, v228
	v_add_f32_e32 v229, 1.0, v229
	v_add_f32_e32 v230, 1.0, v230
	v_add_f32_e32 v231, 1.0, v231
	v_rcp_f32_e32 v224, v224
	v_rcp_f32_e32 v225, v225
	v_rcp_f32_e32 v226, v226
	v_rcp_f32_e32 v227, v227
	v_rcp_f32_e32 v228, v228
	v_rcp_f32_e32 v229, v229
	v_rcp_f32_e32 v230, v230
	v_rcp_f32_e32 v231, v231
	v_cvt_pk_bf16_f32 v224, v224, v225
	v_cvt_pk_bf16_f32 v225, v226, v227
	v_cvt_pk_bf16_f32 v226, v228, v229
	v_cvt_pk_bf16_f32 v227, v230, v231
	global_store_dwordx4 v236, v[224:227], s[100:101] nt
	v_mul_f32_e32 v170, 0xbfb8aa3b, v84
	v_mul_f32_e32 v171, 0xbfb8aa3b, v85
	v_mul_f32_e32 v172, 0xbfb8aa3b, v86
	v_mul_f32_e32 v173, 0xbfb8aa3b, v87
	v_mul_f32_e32 v174, 0xbfb8aa3b, v80
	v_mul_f32_e32 v175, 0xbfb8aa3b, v81
	v_mul_f32_e32 v176, 0xbfb8aa3b, v82
	v_mul_f32_e32 v177, 0xbfb8aa3b, v83
	v_exp_f32_e32 v170, v170
	v_exp_f32_e32 v171, v171
	v_exp_f32_e32 v172, v172
	v_exp_f32_e32 v173, v173
	v_exp_f32_e32 v174, v174
	v_exp_f32_e32 v175, v175
	v_exp_f32_e32 v176, v176
	v_exp_f32_e32 v177, v177
	v_add_f32_e32 v170, 1.0, v170
	v_add_f32_e32 v171, 1.0, v171
	v_add_f32_e32 v172, 1.0, v172
	v_add_f32_e32 v173, 1.0, v173
	v_add_f32_e32 v174, 1.0, v174
	v_add_f32_e32 v175, 1.0, v175
	v_add_f32_e32 v176, 1.0, v176
	v_add_f32_e32 v177, 1.0, v177
	v_rcp_f32_e32 v170, v170
	v_rcp_f32_e32 v171, v171
	v_rcp_f32_e32 v172, v172
	v_rcp_f32_e32 v173, v173
	v_rcp_f32_e32 v174, v174
	v_rcp_f32_e32 v175, v175
	v_rcp_f32_e32 v176, v176
	v_rcp_f32_e32 v177, v177
	v_cvt_pk_bf16_f32 v170, v170, v171
	v_cvt_pk_bf16_f32 v171, v172, v173
	v_cvt_pk_bf16_f32 v172, v174, v175
	v_cvt_pk_bf16_f32 v173, v176, v177
	global_store_dwordx4 v237, v[170:173], s[100:101] nt
	v_mul_f32_e32 v178, 0xbfb8aa3b, v76
	v_mul_f32_e32 v179, 0xbfb8aa3b, v77
	v_mul_f32_e32 v180, 0xbfb8aa3b, v78
	v_mul_f32_e32 v181, 0xbfb8aa3b, v79
	v_mul_f32_e32 v182, 0xbfb8aa3b, v72
	v_mul_f32_e32 v183, 0xbfb8aa3b, v73
	v_mul_f32_e32 v184, 0xbfb8aa3b, v74
	v_mul_f32_e32 v185, 0xbfb8aa3b, v75
	v_exp_f32_e32 v178, v178
	v_exp_f32_e32 v179, v179
	v_exp_f32_e32 v180, v180
	v_exp_f32_e32 v181, v181
	v_exp_f32_e32 v182, v182
	v_exp_f32_e32 v183, v183
	v_exp_f32_e32 v184, v184
	v_exp_f32_e32 v185, v185
	v_add_f32_e32 v178, 1.0, v178
	v_add_f32_e32 v179, 1.0, v179
	v_add_f32_e32 v180, 1.0, v180
	v_add_f32_e32 v181, 1.0, v181
	v_add_f32_e32 v182, 1.0, v182
	v_add_f32_e32 v183, 1.0, v183
	v_add_f32_e32 v184, 1.0, v184
	v_add_f32_e32 v185, 1.0, v185
	v_rcp_f32_e32 v178, v178
	v_rcp_f32_e32 v179, v179
	v_rcp_f32_e32 v180, v180
	v_rcp_f32_e32 v181, v181
	v_rcp_f32_e32 v182, v182
	v_rcp_f32_e32 v183, v183
	v_rcp_f32_e32 v184, v184
	v_rcp_f32_e32 v185, v185
	v_cvt_pk_bf16_f32 v178, v178, v179
	v_cvt_pk_bf16_f32 v179, v180, v181
	v_cvt_pk_bf16_f32 v180, v182, v183
	v_cvt_pk_bf16_f32 v181, v184, v185
	global_store_dwordx4 v238, v[178:181], s[100:101] nt
	v_mul_f32_e32 v186, 0xbfb8aa3b, v68
	v_mul_f32_e32 v187, 0xbfb8aa3b, v69
	v_mul_f32_e32 v188, 0xbfb8aa3b, v70
	v_mul_f32_e32 v189, 0xbfb8aa3b, v71
	v_mul_f32_e32 v212, 0xbfb8aa3b, v64
	v_mul_f32_e32 v213, 0xbfb8aa3b, v65
	v_mul_f32_e32 v214, 0xbfb8aa3b, v66
	v_mul_f32_e32 v215, 0xbfb8aa3b, v67
	v_exp_f32_e32 v186, v186
	v_exp_f32_e32 v187, v187
	v_exp_f32_e32 v188, v188
	v_exp_f32_e32 v189, v189
	v_exp_f32_e32 v212, v212
	v_exp_f32_e32 v213, v213
	v_exp_f32_e32 v214, v214
	v_exp_f32_e32 v215, v215
	v_add_f32_e32 v186, 1.0, v186
	v_add_f32_e32 v187, 1.0, v187
	v_add_f32_e32 v188, 1.0, v188
	v_add_f32_e32 v189, 1.0, v189
	v_add_f32_e32 v212, 1.0, v212
	v_add_f32_e32 v213, 1.0, v213
	v_add_f32_e32 v214, 1.0, v214
	v_add_f32_e32 v215, 1.0, v215
	v_rcp_f32_e32 v186, v186
	v_rcp_f32_e32 v187, v187
	v_rcp_f32_e32 v188, v188
	v_rcp_f32_e32 v189, v189
	v_rcp_f32_e32 v212, v212
	v_rcp_f32_e32 v213, v213
	v_rcp_f32_e32 v214, v214
	v_rcp_f32_e32 v215, v215
	v_cvt_pk_bf16_f32 v186, v186, v187
	v_cvt_pk_bf16_f32 v187, v188, v189
	v_cvt_pk_bf16_f32 v188, v212, v213
	v_cvt_pk_bf16_f32 v189, v214, v215
	global_store_dwordx4 v239, v[186:189], s[100:101] nt
	v_mul_f32_e32 v216, 0xbfb8aa3b, v60
	v_mul_f32_e32 v217, 0xbfb8aa3b, v61
	v_mul_f32_e32 v218, 0xbfb8aa3b, v62
	v_mul_f32_e32 v219, 0xbfb8aa3b, v63
	v_mul_f32_e32 v220, 0xbfb8aa3b, v56
	v_mul_f32_e32 v221, 0xbfb8aa3b, v57
	v_mul_f32_e32 v222, 0xbfb8aa3b, v58
	v_mul_f32_e32 v223, 0xbfb8aa3b, v59
	v_exp_f32_e32 v216, v216
	v_exp_f32_e32 v217, v217
	v_exp_f32_e32 v218, v218
	v_exp_f32_e32 v219, v219
	v_exp_f32_e32 v220, v220
	v_exp_f32_e32 v221, v221
	v_exp_f32_e32 v222, v222
	v_exp_f32_e32 v223, v223
	v_add_f32_e32 v216, 1.0, v216
	v_add_f32_e32 v217, 1.0, v217
	v_add_f32_e32 v218, 1.0, v218
	v_add_f32_e32 v219, 1.0, v219
	v_add_f32_e32 v220, 1.0, v220
	v_add_f32_e32 v221, 1.0, v221
	v_add_f32_e32 v222, 1.0, v222
	v_add_f32_e32 v223, 1.0, v223
	v_rcp_f32_e32 v216, v216
	v_rcp_f32_e32 v217, v217
	v_rcp_f32_e32 v218, v218
	v_rcp_f32_e32 v219, v219
	v_rcp_f32_e32 v220, v220
	v_rcp_f32_e32 v221, v221
	v_rcp_f32_e32 v222, v222
	v_rcp_f32_e32 v223, v223
	v_cvt_pk_bf16_f32 v216, v216, v217
	v_cvt_pk_bf16_f32 v217, v218, v219
	v_cvt_pk_bf16_f32 v218, v220, v221
	v_cvt_pk_bf16_f32 v219, v222, v223
	global_store_dwordx4 v236, v[216:219], s[98:99] offset:256 nt
	v_mul_f32_e32 v224, 0xbfb8aa3b, v52
	v_mul_f32_e32 v225, 0xbfb8aa3b, v53
	v_mul_f32_e32 v226, 0xbfb8aa3b, v54
	v_mul_f32_e32 v227, 0xbfb8aa3b, v55
	v_mul_f32_e32 v228, 0xbfb8aa3b, v48
	v_mul_f32_e32 v229, 0xbfb8aa3b, v49
	v_mul_f32_e32 v230, 0xbfb8aa3b, v50
	v_mul_f32_e32 v231, 0xbfb8aa3b, v51
	v_exp_f32_e32 v224, v224
	v_exp_f32_e32 v225, v225
	v_exp_f32_e32 v226, v226
; __device__ __forceinline__ float sigmoidf_(float x) { return __builtin_amdgcn_rcpf(1.f + __builtin_amdgcn_exp2f(-1.4426950408889634f * x)); }
; __device__ __forceinline__ u32x4 pack8v(f32x4 a, f32x4 b) { u32x4 w; w.x = cvtpk(a[0], a[1]); w.y = cvtpk(a[2], a[3]); w.z = cvtpk(b[0], b[1]); w.w = cvtpk(b[2], b[3]); return w; }
;     __device__ __forceinline__ void operator()(const Acc& acc, const Unit& u, int wr, int wc, int fr, int fq) const {
;     ...
;                     } else if (kind == 1) {
; #pragma unroll
;                         for (int e = 0; e < 4; ++e) { v0[e] = sigmoidf_(v0[e]); v1[e] = sigmoidf_(v1[e]); }
;                         __builtin_nontemporal_store(pack8v(v0, v1), (u32x4*)(base + (size_t)row * 4096 + d));
	v_exp_f32_e32 v227, v227
	v_exp_f32_e32 v228, v228
	v_exp_f32_e32 v229, v229
	v_exp_f32_e32 v230, v230
	v_exp_f32_e32 v231, v231
	v_add_f32_e32 v224, 1.0, v224
	v_add_f32_e32 v225, 1.0, v225
	v_add_f32_e32 v226, 1.0, v226
	v_add_f32_e32 v227, 1.0, v227
	v_add_f32_e32 v228, 1.0, v228
	v_add_f32_e32 v229, 1.0, v229
	v_add_f32_e32 v230, 1.0, v230
	v_add_f32_e32 v231, 1.0, v231
	v_rcp_f32_e32 v224, v224
	v_rcp_f32_e32 v225, v225
	v_rcp_f32_e32 v226, v226
	v_rcp_f32_e32 v227, v227
	v_rcp_f32_e32 v228, v228
	v_rcp_f32_e32 v229, v229
	v_rcp_f32_e32 v230, v230
	v_rcp_f32_e32 v231, v231
	v_cvt_pk_bf16_f32 v224, v224, v225
	v_cvt_pk_bf16_f32 v225, v226, v227
	v_cvt_pk_bf16_f32 v226, v228, v229
	v_cvt_pk_bf16_f32 v227, v230, v231
	global_store_dwordx4 v237, v[224:227], s[98:99] offset:256 nt
	v_mul_f32_e32 v170, 0xbfb8aa3b, v44
	v_mul_f32_e32 v171, 0xbfb8aa3b, v45
	v_mul_f32_e32 v172, 0xbfb8aa3b, v46
	v_mul_f32_e32 v173, 0xbfb8aa3b, v47
	v_mul_f32_e32 v174, 0xbfb8aa3b, v40
	v_mul_f32_e32 v175, 0xbfb8aa3b, v41
	v_mul_f32_e32 v176, 0xbfb8aa3b, v42
	v_mul_f32_e32 v177, 0xbfb8aa3b, v43
	v_exp_f32_e32 v170, v170
	v_exp_f32_e32 v171, v171
	v_exp_f32_e32 v172, v172
	v_exp_f32_e32 v173, v173
	v_exp_f32_e32 v174, v174
	v_exp_f32_e32 v175, v175
	v_exp_f32_e32 v176, v176
	v_exp_f32_e32 v177, v177
	v_add_f32_e32 v170, 1.0, v170
	v_add_f32_e32 v171, 1.0, v171
	v_add_f32_e32 v172, 1.0, v172
	v_add_f32_e32 v173, 1.0, v173
	v_add_f32_e32 v174, 1.0, v174
	v_add_f32_e32 v175, 1.0, v175
	v_add_f32_e32 v176, 1.0, v176
	v_add_f32_e32 v177, 1.0, v177
	v_rcp_f32_e32 v170, v170
	v_rcp_f32_e32 v171, v171
	v_rcp_f32_e32 v172, v172
	v_rcp_f32_e32 v173, v173
	v_rcp_f32_e32 v174, v174
	v_rcp_f32_e32 v175, v175
	v_rcp_f32_e32 v176, v176
	v_rcp_f32_e32 v177, v177
	v_cvt_pk_bf16_f32 v170, v170, v171
	v_cvt_pk_bf16_f32 v171, v172, v173
	v_cvt_pk_bf16_f32 v172, v174, v175
	v_cvt_pk_bf16_f32 v173, v176, v177
	global_store_dwordx4 v238, v[170:173], s[98:99] offset:256 nt
	v_mul_f32_e32 v178, 0xbfb8aa3b, v36
	v_mul_f32_e32 v179, 0xbfb8aa3b, v37
	v_mul_f32_e32 v180, 0xbfb8aa3b, v38
	v_mul_f32_e32 v181, 0xbfb8aa3b, v39
	v_mul_f32_e32 v182, 0xbfb8aa3b, v32
	v_mul_f32_e32 v183, 0xbfb8aa3b, v33
	v_mul_f32_e32 v184, 0xbfb8aa3b, v34
	v_mul_f32_e32 v185, 0xbfb8aa3b, v35
	v_exp_f32_e32 v178, v178
	v_exp_f32_e32 v179, v179
	v_exp_f32_e32 v180, v180
	v_exp_f32_e32 v181, v181
	v_exp_f32_e32 v182, v182
	v_exp_f32_e32 v183, v183
	v_exp_f32_e32 v184, v184
	v_exp_f32_e32 v185, v185
	v_add_f32_e32 v178, 1.0, v178
	v_add_f32_e32 v179, 1.0, v179
	v_add_f32_e32 v180, 1.0, v180
	v_add_f32_e32 v181, 1.0, v181
	v_add_f32_e32 v182, 1.0, v182
	v_add_f32_e32 v183, 1.0, v183
	v_add_f32_e32 v184, 1.0, v184
	v_add_f32_e32 v185, 1.0, v185
	v_rcp_f32_e32 v178, v178
	v_rcp_f32_e32 v179, v179
	v_rcp_f32_e32 v180, v180
	v_rcp_f32_e32 v181, v181
	v_rcp_f32_e32 v182, v182
	v_rcp_f32_e32 v183, v183
	v_rcp_f32_e32 v184, v184
	v_rcp_f32_e32 v185, v185
	v_cvt_pk_bf16_f32 v178, v178, v179
	v_cvt_pk_bf16_f32 v179, v180, v181
	v_cvt_pk_bf16_f32 v180, v182, v183
	v_cvt_pk_bf16_f32 v181, v184, v185
	global_store_dwordx4 v239, v[178:181], s[98:99] offset:256 nt
	v_mul_f32_e32 v186, 0xbfb8aa3b, v28
	v_mul_f32_e32 v187, 0xbfb8aa3b, v29
	v_mul_f32_e32 v188, 0xbfb8aa3b, v30
	v_mul_f32_e32 v189, 0xbfb8aa3b, v31
	v_mul_f32_e32 v212, 0xbfb8aa3b, v24
	v_mul_f32_e32 v213, 0xbfb8aa3b, v25
	v_mul_f32_e32 v214, 0xbfb8aa3b, v26
	v_mul_f32_e32 v215, 0xbfb8aa3b, v27
	v_exp_f32_e32 v186, v186
	v_exp_f32_e32 v187, v187
	v_exp_f32_e32 v188, v188
	v_exp_f32_e32 v189, v189
	v_exp_f32_e32 v212, v212
	v_exp_f32_e32 v213, v213
	v_exp_f32_e32 v214, v214
	v_exp_f32_e32 v215, v215
	v_add_f32_e32 v186, 1.0, v186
	v_add_f32_e32 v187, 1.0, v187
	v_add_f32_e32 v188, 1.0, v188
	v_add_f32_e32 v189, 1.0, v189
	v_add_f32_e32 v212, 1.0, v212
	v_add_f32_e32 v213, 1.0, v213
	v_add_f32_e32 v214, 1.0, v214
	v_add_f32_e32 v215, 1.0, v215
	v_rcp_f32_e32 v186, v186
; __device__ __forceinline__ u32x4 pack8v(f32x4 a, f32x4 b) { u32x4 w; w.x = cvtpk(a[0], a[1]); w.y = cvtpk(a[2], a[3]); w.z = cvtpk(b[0], b[1]); w.w = cvtpk(b[2], b[3]); return w; }
; __device__ __forceinline__ float sigmoidf_(float x) { return __builtin_amdgcn_rcpf(1.f + __builtin_amdgcn_exp2f(-1.4426950408889634f * x)); }
;     __device__ __forceinline__ void operator()(const Acc& acc, const Unit& u, int wr, int wc, int fr, int fq) const {
;     ...
;                     } else if (kind == 1) {
; #pragma unroll
;                         for (int e = 0; e < 4; ++e) { v0[e] = sigmoidf_(v0[e]); v1[e] = sigmoidf_(v1[e]); }
;                         __builtin_nontemporal_store(pack8v(v0, v1), (u32x4*)(base + (size_t)row * 4096 + d));
	v_rcp_f32_e32 v187, v187
	v_rcp_f32_e32 v188, v188
	v_rcp_f32_e32 v189, v189
	v_rcp_f32_e32 v212, v212
	v_rcp_f32_e32 v213, v213
	v_rcp_f32_e32 v214, v214
	v_rcp_f32_e32 v215, v215
	v_cvt_pk_bf16_f32 v186, v186, v187
	v_cvt_pk_bf16_f32 v187, v188, v189
	v_cvt_pk_bf16_f32 v188, v212, v213
	v_cvt_pk_bf16_f32 v189, v214, v215
	global_store_dwordx4 v236, v[186:189], s[100:101] offset:256 nt
	v_mul_f32_e32 v216, 0xbfb8aa3b, v20
	v_mul_f32_e32 v217, 0xbfb8aa3b, v21
	v_mul_f32_e32 v218, 0xbfb8aa3b, v22
	v_mul_f32_e32 v219, 0xbfb8aa3b, v23
	v_mul_f32_e32 v220, 0xbfb8aa3b, v16
	v_mul_f32_e32 v221, 0xbfb8aa3b, v17
	v_mul_f32_e32 v222, 0xbfb8aa3b, v18
	v_mul_f32_e32 v223, 0xbfb8aa3b, v19
	v_exp_f32_e32 v216, v216
	v_exp_f32_e32 v217, v217
	v_exp_f32_e32 v218, v218
	v_exp_f32_e32 v219, v219
	v_exp_f32_e32 v220, v220
	v_exp_f32_e32 v221, v221
	v_exp_f32_e32 v222, v222
	v_exp_f32_e32 v223, v223
	v_add_f32_e32 v216, 1.0, v216
	v_add_f32_e32 v217, 1.0, v217
	v_add_f32_e32 v218, 1.0, v218
	v_add_f32_e32 v219, 1.0, v219
	v_add_f32_e32 v220, 1.0, v220
	v_add_f32_e32 v221, 1.0, v221
	v_add_f32_e32 v222, 1.0, v222
	v_add_f32_e32 v223, 1.0, v223
	v_rcp_f32_e32 v216, v216
	v_rcp_f32_e32 v217, v217
	v_rcp_f32_e32 v218, v218
	v_rcp_f32_e32 v219, v219
	v_rcp_f32_e32 v220, v220
	v_rcp_f32_e32 v221, v221
	v_rcp_f32_e32 v222, v222
	v_rcp_f32_e32 v223, v223
	v_cvt_pk_bf16_f32 v216, v216, v217
	v_cvt_pk_bf16_f32 v217, v218, v219
	v_cvt_pk_bf16_f32 v218, v220, v221
	v_cvt_pk_bf16_f32 v219, v222, v223
	global_store_dwordx4 v237, v[216:219], s[100:101] offset:256 nt
	v_mul_f32_e32 v224, 0xbfb8aa3b, v12
	v_mul_f32_e32 v225, 0xbfb8aa3b, v13
	v_mul_f32_e32 v226, 0xbfb8aa3b, v14
	v_mul_f32_e32 v227, 0xbfb8aa3b, v15
	v_mul_f32_e32 v228, 0xbfb8aa3b, v8
	v_mul_f32_e32 v229, 0xbfb8aa3b, v9
	v_mul_f32_e32 v230, 0xbfb8aa3b, v10
	v_mul_f32_e32 v231, 0xbfb8aa3b, v11
	v_exp_f32_e32 v224, v224
	v_exp_f32_e32 v225, v225
	v_exp_f32_e32 v226, v226
	v_exp_f32_e32 v227, v227
	v_exp_f32_e32 v228, v228
	v_exp_f32_e32 v229, v229
	v_exp_f32_e32 v230, v230
	v_exp_f32_e32 v231, v231
	v_add_f32_e32 v224, 1.0, v224
	v_add_f32_e32 v225, 1.0, v225
	v_add_f32_e32 v226, 1.0, v226
	v_add_f32_e32 v227, 1.0, v227
	v_add_f32_e32 v228, 1.0, v228
	v_add_f32_e32 v229, 1.0, v229
	v_add_f32_e32 v230, 1.0, v230
	v_add_f32_e32 v231, 1.0, v231
	v_rcp_f32_e32 v224, v224
	v_rcp_f32_e32 v225, v225
	v_rcp_f32_e32 v226, v226
	v_rcp_f32_e32 v227, v227
	v_rcp_f32_e32 v228, v228
	v_rcp_f32_e32 v229, v229
	v_rcp_f32_e32 v230, v230
	v_rcp_f32_e32 v231, v231
	v_cvt_pk_bf16_f32 v224, v224, v225
	v_cvt_pk_bf16_f32 v225, v226, v227
	v_cvt_pk_bf16_f32 v226, v228, v229
	v_cvt_pk_bf16_f32 v227, v230, v231
	global_store_dwordx4 v238, v[224:227], s[100:101] offset:256 nt
	v_mul_f32_e32 v170, 0xbfb8aa3b, v4
	v_mul_f32_e32 v171, 0xbfb8aa3b, v5
	v_mul_f32_e32 v172, 0xbfb8aa3b, v6
	v_mul_f32_e32 v173, 0xbfb8aa3b, v7
	v_mul_f32_e32 v174, 0xbfb8aa3b, v0
	v_mul_f32_e32 v175, 0xbfb8aa3b, v1
	v_mul_f32_e32 v176, 0xbfb8aa3b, v2
	v_mul_f32_e32 v177, 0xbfb8aa3b, v3
	v_exp_f32_e32 v170, v170
	v_exp_f32_e32 v171, v171
	v_exp_f32_e32 v172, v172
	v_exp_f32_e32 v173, v173
	v_exp_f32_e32 v174, v174
	v_exp_f32_e32 v175, v175
	v_exp_f32_e32 v176, v176
	v_exp_f32_e32 v177, v177
	v_add_f32_e32 v170, 1.0, v170
	v_add_f32_e32 v171, 1.0, v171
	v_add_f32_e32 v172, 1.0, v172
	v_add_f32_e32 v173, 1.0, v173
	v_add_f32_e32 v174, 1.0, v174
	v_add_f32_e32 v175, 1.0, v175
	v_add_f32_e32 v176, 1.0, v176
	v_add_f32_e32 v177, 1.0, v177
	v_rcp_f32_e32 v170, v170
	v_rcp_f32_e32 v171, v171
	v_rcp_f32_e32 v172, v172
	v_rcp_f32_e32 v173, v173
	v_rcp_f32_e32 v174, v174
	v_rcp_f32_e32 v175, v175
	v_rcp_f32_e32 v176, v176
	v_rcp_f32_e32 v177, v177
	v_cvt_pk_bf16_f32 v170, v170, v171
	v_cvt_pk_bf16_f32 v171, v172, v173
	v_cvt_pk_bf16_f32 v172, v174, v175
	v_cvt_pk_bf16_f32 v173, v176, v177
	global_store_dwordx4 v239, v[170:173], s[100:101] offset:256 nt
	s_branch .LBB0_290
